# P3: K-midpoint gate rescale rewritten (16 loads in flight, halves aligned by extra barriers) and final-epilogue gate loads batched with counted waits
# speedup vs baseline: 1.0290x; 1.0070x over previous
.LBB0_813:
	s_cmpk_lg_i32 s24, 0x400
	s_cbranch_scc1 .LBB0_812
	v_mov_b32_e32 v2, v164
	v_mad_i64_i32 v[2:3], s[2:3], v2, s42, v[166:167]
	global_load_dwordx4 v[132:135], v[2:3], off
	global_load_dwordx4 v[136:139], v[2:3], off offset:256
	v_add_u32_e32 v2, 16, v164
	v_mad_i64_i32 v[2:3], s[2:3], v2, s42, v[166:167]
	global_load_dwordx4 v[140:143], v[2:3], off
	global_load_dwordx4 v[144:147], v[2:3], off offset:256
	v_add_u32_e32 v2, 32, v164
	v_mad_i64_i32 v[2:3], s[2:3], v2, s42, v[166:167]
	global_load_dwordx4 v[178:181], v[2:3], off
	global_load_dwordx4 v[182:185], v[2:3], off offset:256
	v_add_u32_e32 v2, 48, v164
	v_mad_i64_i32 v[2:3], s[2:3], v2, s42, v[166:167]
	global_load_dwordx4 v[186:189], v[2:3], off
	global_load_dwordx4 v[190:193], v[2:3], off offset:256
	v_add_u32_e32 v2, 0x80, v164
	v_mad_i64_i32 v[2:3], s[2:3], v2, s42, v[166:167]
	global_load_dwordx4 v[194:197], v[2:3], off
	global_load_dwordx4 v[198:201], v[2:3], off offset:256
	v_add_u32_e32 v2, 0x90, v164
	v_mad_i64_i32 v[2:3], s[2:3], v2, s42, v[166:167]
	global_load_dwordx4 v[202:205], v[2:3], off
	global_load_dwordx4 v[206:209], v[2:3], off offset:256
	v_add_u32_e32 v2, 0xa0, v164
	v_mad_i64_i32 v[2:3], s[2:3], v2, s42, v[166:167]
	global_load_dwordx4 v[210:213], v[2:3], off
	global_load_dwordx4 v[216:219], v[2:3], off offset:256
	v_add_u32_e32 v2, 0xb0, v164
	v_mad_i64_i32 v[2:3], s[2:3], v2, s42, v[166:167]
	global_load_dwordx4 v[220:223], v[2:3], off
	global_load_dwordx4 v[224:227], v[2:3], off offset:256
	s_and_b64 vcc, exec, s[12:13]
	s_cbranch_vccz .Lp3mid_a
	s_barrier
.Lp3mid_a:
	s_waitcnt vmcnt(15)
	v_cvt_f32_ubyte0_e32 v247, v134
	v_cvt_f32_ubyte1_e32 v248, v134
	v_cvt_f32_ubyte2_e32 v249, v134
	v_cvt_f32_ubyte3_e32 v250, v134
	v_max_f32_e32 v247, 1.0, v247
	v_max_f32_e32 v248, 1.0, v248
	v_max_f32_e32 v249, 1.0, v249
	v_max_f32_e32 v250, 1.0, v250
	v_cvt_f32_ubyte0_e32 v251, v132
	v_cvt_f32_ubyte1_e32 v252, v132
	v_cvt_f32_ubyte2_e32 v253, v132
	v_cvt_f32_ubyte3_e32 v254, v132
	v_rcp_f32_e32 v247, v247
	v_rcp_f32_e32 v248, v248
	v_rcp_f32_e32 v249, v249
	v_rcp_f32_e32 v250, v250
	v_mul_f32_e32 v251, v251, v247
	v_mul_f32_e32 v252, v252, v248
	v_mul_f32_e32 v253, v253, v249
	v_mul_f32_e32 v254, v254, v250
	v_mul_f32_e32 v128, v128, v251
	v_mul_f32_e32 v129, v129, v252
	v_mul_f32_e32 v130, v130, v253
	v_mul_f32_e32 v131, v131, v254
	v_cvt_f32_ubyte0_e32 v247, v135
	v_cvt_f32_ubyte1_e32 v248, v135
	v_cvt_f32_ubyte2_e32 v249, v135
	v_cvt_f32_ubyte3_e32 v250, v135
	v_max_f32_e32 v247, 1.0, v247
	v_max_f32_e32 v248, 1.0, v248
	v_max_f32_e32 v249, 1.0, v249
	v_max_f32_e32 v250, 1.0, v250
	v_cvt_f32_ubyte0_e32 v251, v133
	v_cvt_f32_ubyte1_e32 v252, v133
	v_cvt_f32_ubyte2_e32 v253, v133
	v_cvt_f32_ubyte3_e32 v254, v133
	v_rcp_f32_e32 v247, v247
	v_rcp_f32_e32 v248, v248
	v_rcp_f32_e32 v249, v249
	v_rcp_f32_e32 v250, v250
	v_mul_f32_e32 v251, v251, v247
	v_mul_f32_e32 v252, v252, v248
	v_mul_f32_e32 v253, v253, v249
	v_mul_f32_e32 v254, v254, v250
	v_mul_f32_e32 v124, v124, v251
	v_mul_f32_e32 v125, v125, v252
	v_mul_f32_e32 v126, v126, v253
	v_mul_f32_e32 v127, v127, v254
	s_waitcnt vmcnt(14)
	v_cvt_f32_ubyte0_e32 v247, v138
	v_cvt_f32_ubyte1_e32 v248, v138
	v_cvt_f32_ubyte2_e32 v249, v138
	v_cvt_f32_ubyte3_e32 v250, v138
	v_max_f32_e32 v247, 1.0, v247
	v_max_f32_e32 v248, 1.0, v248
	v_max_f32_e32 v249, 1.0, v249
	v_max_f32_e32 v250, 1.0, v250
	v_cvt_f32_ubyte0_e32 v251, v136
	v_cvt_f32_ubyte1_e32 v252, v136
	v_cvt_f32_ubyte2_e32 v253, v136
	v_cvt_f32_ubyte3_e32 v254, v136
	v_rcp_f32_e32 v247, v247
	v_rcp_f32_e32 v248, v248
	v_rcp_f32_e32 v249, v249
	v_rcp_f32_e32 v250, v250
	v_mul_f32_e32 v251, v251, v247
	v_mul_f32_e32 v252, v252, v248
	v_mul_f32_e32 v253, v253, v249
	v_mul_f32_e32 v254, v254, v250
	v_mul_f32_e32 v120, v120, v251
	v_mul_f32_e32 v121, v121, v252
	v_mul_f32_e32 v122, v122, v253
	v_mul_f32_e32 v123, v123, v254
	v_cvt_f32_ubyte0_e32 v247, v139
	v_cvt_f32_ubyte1_e32 v248, v139
	v_cvt_f32_ubyte2_e32 v249, v139
	v_cvt_f32_ubyte3_e32 v250, v139
	v_max_f32_e32 v247, 1.0, v247
	v_max_f32_e32 v248, 1.0, v248
	v_max_f32_e32 v249, 1.0, v249
	v_max_f32_e32 v250, 1.0, v250
	v_cvt_f32_ubyte0_e32 v251, v137
	v_cvt_f32_ubyte1_e32 v252, v137
	v_cvt_f32_ubyte2_e32 v253, v137
	v_cvt_f32_ubyte3_e32 v254, v137
	v_rcp_f32_e32 v247, v247
	v_rcp_f32_e32 v248, v248
	v_rcp_f32_e32 v249, v249
	v_rcp_f32_e32 v250, v250
	v_mul_f32_e32 v251, v251, v247
	v_mul_f32_e32 v252, v252, v248
	v_mul_f32_e32 v253, v253, v249
	v_mul_f32_e32 v254, v254, v250
	v_mul_f32_e32 v116, v116, v251
	v_mul_f32_e32 v117, v117, v252
	v_mul_f32_e32 v118, v118, v253
	v_mul_f32_e32 v119, v119, v254
	s_waitcnt vmcnt(13)
	v_cvt_f32_ubyte0_e32 v247, v142
	v_cvt_f32_ubyte1_e32 v248, v142
	v_cvt_f32_ubyte2_e32 v249, v142
	v_cvt_f32_ubyte3_e32 v250, v142
	v_max_f32_e32 v247, 1.0, v247
	v_max_f32_e32 v248, 1.0, v248
	v_max_f32_e32 v249, 1.0, v249
	v_max_f32_e32 v250, 1.0, v250
	v_cvt_f32_ubyte0_e32 v251, v140
	v_cvt_f32_ubyte1_e32 v252, v140
	v_cvt_f32_ubyte2_e32 v253, v140
	v_cvt_f32_ubyte3_e32 v254, v140
	v_rcp_f32_e32 v247, v247
	v_rcp_f32_e32 v248, v248
	v_rcp_f32_e32 v249, v249
	v_rcp_f32_e32 v250, v250
	v_mul_f32_e32 v251, v251, v247
	v_mul_f32_e32 v252, v252, v248
	v_mul_f32_e32 v253, v253, v249
	v_mul_f32_e32 v254, v254, v250
	v_mul_f32_e32 v112, v112, v251
	v_mul_f32_e32 v113, v113, v252
	v_mul_f32_e32 v114, v114, v253
	v_mul_f32_e32 v115, v115, v254
	v_cvt_f32_ubyte0_e32 v247, v143
	v_cvt_f32_ubyte1_e32 v248, v143
	v_cvt_f32_ubyte2_e32 v249, v143
	v_cvt_f32_ubyte3_e32 v250, v143
	v_max_f32_e32 v247, 1.0, v247
	v_max_f32_e32 v248, 1.0, v248
	v_max_f32_e32 v249, 1.0, v249
	v_max_f32_e32 v250, 1.0, v250
	v_cvt_f32_ubyte0_e32 v251, v141
	v_cvt_f32_ubyte1_e32 v252, v141
	v_cvt_f32_ubyte2_e32 v253, v141
	v_cvt_f32_ubyte3_e32 v254, v141
	v_rcp_f32_e32 v247, v247
	v_rcp_f32_e32 v248, v248
	v_rcp_f32_e32 v249, v249
	v_rcp_f32_e32 v250, v250
	v_mul_f32_e32 v251, v251, v247
	v_mul_f32_e32 v252, v252, v248
	v_mul_f32_e32 v253, v253, v249
	v_mul_f32_e32 v254, v254, v250
	v_mul_f32_e32 v108, v108, v251
	v_mul_f32_e32 v109, v109, v252
	v_mul_f32_e32 v110, v110, v253
	v_mul_f32_e32 v111, v111, v254
	s_waitcnt vmcnt(12)
	v_cvt_f32_ubyte0_e32 v247, v146
	v_cvt_f32_ubyte1_e32 v248, v146
	v_cvt_f32_ubyte2_e32 v249, v146
	v_cvt_f32_ubyte3_e32 v250, v146
	v_max_f32_e32 v247, 1.0, v247
	v_max_f32_e32 v248, 1.0, v248
	v_max_f32_e32 v249, 1.0, v249
	v_max_f32_e32 v250, 1.0, v250
	v_cvt_f32_ubyte0_e32 v251, v144
	v_cvt_f32_ubyte1_e32 v252, v144
	v_cvt_f32_ubyte2_e32 v253, v144
	v_cvt_f32_ubyte3_e32 v254, v144
	v_rcp_f32_e32 v247, v247
	v_rcp_f32_e32 v248, v248
	v_rcp_f32_e32 v249, v249
	v_rcp_f32_e32 v250, v250
	v_mul_f32_e32 v251, v251, v247
	v_mul_f32_e32 v252, v252, v248
	v_mul_f32_e32 v253, v253, v249
	v_mul_f32_e32 v254, v254, v250
	v_mul_f32_e32 v104, v104, v251
	v_mul_f32_e32 v105, v105, v252
	v_mul_f32_e32 v106, v106, v253
	v_mul_f32_e32 v107, v107, v254
	v_cvt_f32_ubyte0_e32 v247, v147
	v_cvt_f32_ubyte1_e32 v248, v147
	v_cvt_f32_ubyte2_e32 v249, v147
	v_cvt_f32_ubyte3_e32 v250, v147
	v_max_f32_e32 v247, 1.0, v247
	v_max_f32_e32 v248, 1.0, v248
	v_max_f32_e32 v249, 1.0, v249
	v_max_f32_e32 v250, 1.0, v250
	v_cvt_f32_ubyte0_e32 v251, v145
	v_cvt_f32_ubyte1_e32 v252, v145
	v_cvt_f32_ubyte2_e32 v253, v145
	v_cvt_f32_ubyte3_e32 v254, v145
	v_rcp_f32_e32 v247, v247
	v_rcp_f32_e32 v248, v248
	v_rcp_f32_e32 v249, v249
	v_rcp_f32_e32 v250, v250
	v_mul_f32_e32 v251, v251, v247
	v_mul_f32_e32 v252, v252, v248
	v_mul_f32_e32 v253, v253, v249
	v_mul_f32_e32 v254, v254, v250
	v_mul_f32_e32 v100, v100, v251
	v_mul_f32_e32 v101, v101, v252
	v_mul_f32_e32 v102, v102, v253
	v_mul_f32_e32 v103, v103, v254
	s_waitcnt vmcnt(11)
	v_cvt_f32_ubyte0_e32 v247, v180
	v_cvt_f32_ubyte1_e32 v248, v180
	v_cvt_f32_ubyte2_e32 v249, v180
	v_cvt_f32_ubyte3_e32 v250, v180
	v_max_f32_e32 v247, 1.0, v247
	v_max_f32_e32 v248, 1.0, v248
	v_max_f32_e32 v249, 1.0, v249
	v_max_f32_e32 v250, 1.0, v250
	v_cvt_f32_ubyte0_e32 v251, v178
	v_cvt_f32_ubyte1_e32 v252, v178
	v_cvt_f32_ubyte2_e32 v253, v178
	v_cvt_f32_ubyte3_e32 v254, v178
	v_rcp_f32_e32 v247, v247
	v_rcp_f32_e32 v248, v248
	v_rcp_f32_e32 v249, v249
	v_rcp_f32_e32 v250, v250
	v_mul_f32_e32 v251, v251, v247
	v_mul_f32_e32 v252, v252, v248
	v_mul_f32_e32 v253, v253, v249
	v_mul_f32_e32 v254, v254, v250
	v_mul_f32_e32 v96, v96, v251
	v_mul_f32_e32 v97, v97, v252
	v_mul_f32_e32 v98, v98, v253
	v_mul_f32_e32 v99, v99, v254
	v_cvt_f32_ubyte0_e32 v247, v181
	v_cvt_f32_ubyte1_e32 v248, v181
	v_cvt_f32_ubyte2_e32 v249, v181
	v_cvt_f32_ubyte3_e32 v250, v181
	v_max_f32_e32 v247, 1.0, v247
	v_max_f32_e32 v248, 1.0, v248
	v_max_f32_e32 v249, 1.0, v249
	v_max_f32_e32 v250, 1.0, v250
	v_cvt_f32_ubyte0_e32 v251, v179
	v_cvt_f32_ubyte1_e32 v252, v179
	v_cvt_f32_ubyte2_e32 v253, v179
	v_cvt_f32_ubyte3_e32 v254, v179
	v_rcp_f32_e32 v247, v247
	v_rcp_f32_e32 v248, v248
	v_rcp_f32_e32 v249, v249
	v_rcp_f32_e32 v250, v250
	v_mul_f32_e32 v251, v251, v247
	v_mul_f32_e32 v252, v252, v248
	v_mul_f32_e32 v253, v253, v249
	v_mul_f32_e32 v254, v254, v250
	v_mul_f32_e32 v92, v92, v251
	v_mul_f32_e32 v93, v93, v252
	v_mul_f32_e32 v94, v94, v253
	v_mul_f32_e32 v95, v95, v254
	s_waitcnt vmcnt(10)
	v_cvt_f32_ubyte0_e32 v247, v184
	v_cvt_f32_ubyte1_e32 v248, v184
	v_cvt_f32_ubyte2_e32 v249, v184
	v_cvt_f32_ubyte3_e32 v250, v184
	v_max_f32_e32 v247, 1.0, v247
	v_max_f32_e32 v248, 1.0, v248
	v_max_f32_e32 v249, 1.0, v249
	v_max_f32_e32 v250, 1.0, v250
	v_cvt_f32_ubyte0_e32 v251, v182
	v_cvt_f32_ubyte1_e32 v252, v182
	v_cvt_f32_ubyte2_e32 v253, v182
	v_cvt_f32_ubyte3_e32 v254, v182
	v_rcp_f32_e32 v247, v247
	v_rcp_f32_e32 v248, v248
	v_rcp_f32_e32 v249, v249
	v_rcp_f32_e32 v250, v250
	v_mul_f32_e32 v251, v251, v247
	v_mul_f32_e32 v252, v252, v248
	v_mul_f32_e32 v253, v253, v249
	v_mul_f32_e32 v254, v254, v250
	v_mul_f32_e32 v88, v88, v251
	v_mul_f32_e32 v89, v89, v252
	v_mul_f32_e32 v90, v90, v253
	v_mul_f32_e32 v91, v91, v254
	v_cvt_f32_ubyte0_e32 v247, v185
	v_cvt_f32_ubyte1_e32 v248, v185
	v_cvt_f32_ubyte2_e32 v249, v185
	v_cvt_f32_ubyte3_e32 v250, v185
	v_max_f32_e32 v247, 1.0, v247
	v_max_f32_e32 v248, 1.0, v248
	v_max_f32_e32 v249, 1.0, v249
	v_max_f32_e32 v250, 1.0, v250
	v_cvt_f32_ubyte0_e32 v251, v183
	v_cvt_f32_ubyte1_e32 v252, v183
	v_cvt_f32_ubyte2_e32 v253, v183
	v_cvt_f32_ubyte3_e32 v254, v183
	v_rcp_f32_e32 v247, v247
	v_rcp_f32_e32 v248, v248
	v_rcp_f32_e32 v249, v249
	v_rcp_f32_e32 v250, v250
	v_mul_f32_e32 v251, v251, v247
	v_mul_f32_e32 v252, v252, v248
	v_mul_f32_e32 v253, v253, v249
	v_mul_f32_e32 v254, v254, v250
	v_mul_f32_e32 v84, v84, v251
	v_mul_f32_e32 v85, v85, v252
	v_mul_f32_e32 v86, v86, v253
	v_mul_f32_e32 v87, v87, v254
	s_waitcnt vmcnt(9)
	v_cvt_f32_ubyte0_e32 v247, v188
	v_cvt_f32_ubyte1_e32 v248, v188
	v_cvt_f32_ubyte2_e32 v249, v188
	v_cvt_f32_ubyte3_e32 v250, v188
	v_max_f32_e32 v247, 1.0, v247
	v_max_f32_e32 v248, 1.0, v248
	v_max_f32_e32 v249, 1.0, v249
	v_max_f32_e32 v250, 1.0, v250
	v_cvt_f32_ubyte0_e32 v251, v186
	v_cvt_f32_ubyte1_e32 v252, v186
	v_cvt_f32_ubyte2_e32 v253, v186
	v_cvt_f32_ubyte3_e32 v254, v186
	v_rcp_f32_e32 v247, v247
	v_rcp_f32_e32 v248, v248
	v_rcp_f32_e32 v249, v249
	v_rcp_f32_e32 v250, v250
	v_mul_f32_e32 v251, v251, v247
	v_mul_f32_e32 v252, v252, v248
	v_mul_f32_e32 v253, v253, v249
	v_mul_f32_e32 v254, v254, v250
	v_mul_f32_e32 v80, v80, v251
	v_mul_f32_e32 v81, v81, v252
	v_mul_f32_e32 v82, v82, v253
	v_mul_f32_e32 v83, v83, v254
	v_cvt_f32_ubyte0_e32 v247, v189
	v_cvt_f32_ubyte1_e32 v248, v189
	v_cvt_f32_ubyte2_e32 v249, v189
	v_cvt_f32_ubyte3_e32 v250, v189
	v_max_f32_e32 v247, 1.0, v247
	v_max_f32_e32 v248, 1.0, v248
	v_max_f32_e32 v249, 1.0, v249
	v_max_f32_e32 v250, 1.0, v250
	v_cvt_f32_ubyte0_e32 v251, v187
	v_cvt_f32_ubyte1_e32 v252, v187
	v_cvt_f32_ubyte2_e32 v253, v187
	v_cvt_f32_ubyte3_e32 v254, v187
	v_rcp_f32_e32 v247, v247
	v_rcp_f32_e32 v248, v248
	v_rcp_f32_e32 v249, v249
	v_rcp_f32_e32 v250, v250
	v_mul_f32_e32 v251, v251, v247
	v_mul_f32_e32 v252, v252, v248
	v_mul_f32_e32 v253, v253, v249
	v_mul_f32_e32 v254, v254, v250
	v_mul_f32_e32 v76, v76, v251
	v_mul_f32_e32 v77, v77, v252
	v_mul_f32_e32 v78, v78, v253
	v_mul_f32_e32 v79, v79, v254
	s_waitcnt vmcnt(8)
	v_cvt_f32_ubyte0_e32 v247, v192
	v_cvt_f32_ubyte1_e32 v248, v192
	v_cvt_f32_ubyte2_e32 v249, v192
	v_cvt_f32_ubyte3_e32 v250, v192
	v_max_f32_e32 v247, 1.0, v247
	v_max_f32_e32 v248, 1.0, v248
	v_max_f32_e32 v249, 1.0, v249
	v_max_f32_e32 v250, 1.0, v250
	v_cvt_f32_ubyte0_e32 v251, v190
	v_cvt_f32_ubyte1_e32 v252, v190
	v_cvt_f32_ubyte2_e32 v253, v190
	v_cvt_f32_ubyte3_e32 v254, v190
	v_rcp_f32_e32 v247, v247
	v_rcp_f32_e32 v248, v248
	v_rcp_f32_e32 v249, v249
	v_rcp_f32_e32 v250, v250
	v_mul_f32_e32 v251, v251, v247
	v_mul_f32_e32 v252, v252, v248
	v_mul_f32_e32 v253, v253, v249
	v_mul_f32_e32 v254, v254, v250
	v_mul_f32_e32 v72, v72, v251
	v_mul_f32_e32 v73, v73, v252
	v_mul_f32_e32 v74, v74, v253
	v_mul_f32_e32 v75, v75, v254
	v_cvt_f32_ubyte0_e32 v247, v193
	v_cvt_f32_ubyte1_e32 v248, v193
	v_cvt_f32_ubyte2_e32 v249, v193
	v_cvt_f32_ubyte3_e32 v250, v193
	v_max_f32_e32 v247, 1.0, v247
	v_max_f32_e32 v248, 1.0, v248
	v_max_f32_e32 v249, 1.0, v249
	v_max_f32_e32 v250, 1.0, v250
	v_cvt_f32_ubyte0_e32 v251, v191
	v_cvt_f32_ubyte1_e32 v252, v191
	v_cvt_f32_ubyte2_e32 v253, v191
	v_cvt_f32_ubyte3_e32 v254, v191
	v_rcp_f32_e32 v247, v247
	v_rcp_f32_e32 v248, v248
	v_rcp_f32_e32 v249, v249
	v_rcp_f32_e32 v250, v250
	v_mul_f32_e32 v251, v251, v247
	v_mul_f32_e32 v252, v252, v248
	v_mul_f32_e32 v253, v253, v249
	v_mul_f32_e32 v254, v254, v250
	v_mul_f32_e32 v68, v68, v251
	v_mul_f32_e32 v69, v69, v252
	v_mul_f32_e32 v70, v70, v253
	v_mul_f32_e32 v71, v71, v254
	s_waitcnt vmcnt(7)
	v_cvt_f32_ubyte0_e32 v247, v196
	v_cvt_f32_ubyte1_e32 v248, v196
	v_cvt_f32_ubyte2_e32 v249, v196
	v_cvt_f32_ubyte3_e32 v250, v196
	v_max_f32_e32 v247, 1.0, v247
	v_max_f32_e32 v248, 1.0, v248
	v_max_f32_e32 v249, 1.0, v249
	v_max_f32_e32 v250, 1.0, v250
	v_cvt_f32_ubyte0_e32 v251, v194
	v_cvt_f32_ubyte1_e32 v252, v194
	v_cvt_f32_ubyte2_e32 v253, v194
	v_cvt_f32_ubyte3_e32 v254, v194
	v_rcp_f32_e32 v247, v247
	v_rcp_f32_e32 v248, v248
	v_rcp_f32_e32 v249, v249
	v_rcp_f32_e32 v250, v250
	v_mul_f32_e32 v251, v251, v247
	v_mul_f32_e32 v252, v252, v248
	v_mul_f32_e32 v253, v253, v249
	v_mul_f32_e32 v254, v254, v250
	v_mul_f32_e32 v64, v64, v251
	v_mul_f32_e32 v65, v65, v252
	v_mul_f32_e32 v66, v66, v253
	v_mul_f32_e32 v67, v67, v254
	v_cvt_f32_ubyte0_e32 v247, v197
	v_cvt_f32_ubyte1_e32 v248, v197
	v_cvt_f32_ubyte2_e32 v249, v197
	v_cvt_f32_ubyte3_e32 v250, v197
	v_max_f32_e32 v247, 1.0, v247
	v_max_f32_e32 v248, 1.0, v248
	v_max_f32_e32 v249, 1.0, v249
	v_max_f32_e32 v250, 1.0, v250
	v_cvt_f32_ubyte0_e32 v251, v195
	v_cvt_f32_ubyte1_e32 v252, v195
	v_cvt_f32_ubyte2_e32 v253, v195
	v_cvt_f32_ubyte3_e32 v254, v195
	v_rcp_f32_e32 v247, v247
	v_rcp_f32_e32 v248, v248
	v_rcp_f32_e32 v249, v249
	v_rcp_f32_e32 v250, v250
	v_mul_f32_e32 v251, v251, v247
	v_mul_f32_e32 v252, v252, v248
	v_mul_f32_e32 v253, v253, v249
	v_mul_f32_e32 v254, v254, v250
	v_mul_f32_e32 v60, v60, v251
	v_mul_f32_e32 v61, v61, v252
	v_mul_f32_e32 v62, v62, v253
	v_mul_f32_e32 v63, v63, v254
	s_waitcnt vmcnt(6)
	v_cvt_f32_ubyte0_e32 v247, v200
	v_cvt_f32_ubyte1_e32 v248, v200
	v_cvt_f32_ubyte2_e32 v249, v200
	v_cvt_f32_ubyte3_e32 v250, v200
	v_max_f32_e32 v247, 1.0, v247
	v_max_f32_e32 v248, 1.0, v248
	v_max_f32_e32 v249, 1.0, v249
	v_max_f32_e32 v250, 1.0, v250
	v_cvt_f32_ubyte0_e32 v251, v198
	v_cvt_f32_ubyte1_e32 v252, v198
	v_cvt_f32_ubyte2_e32 v253, v198
	v_cvt_f32_ubyte3_e32 v254, v198
	v_rcp_f32_e32 v247, v247
	v_rcp_f32_e32 v248, v248
	v_rcp_f32_e32 v249, v249
	v_rcp_f32_e32 v250, v250
	v_mul_f32_e32 v251, v251, v247
	v_mul_f32_e32 v252, v252, v248
	v_mul_f32_e32 v253, v253, v249
	v_mul_f32_e32 v254, v254, v250
	v_mul_f32_e32 v56, v56, v251
	v_mul_f32_e32 v57, v57, v252
	v_mul_f32_e32 v58, v58, v253
	v_mul_f32_e32 v59, v59, v254
	v_cvt_f32_ubyte0_e32 v247, v201
	v_cvt_f32_ubyte1_e32 v248, v201
	v_cvt_f32_ubyte2_e32 v249, v201
	v_cvt_f32_ubyte3_e32 v250, v201
	v_max_f32_e32 v247, 1.0, v247
	v_max_f32_e32 v248, 1.0, v248
	v_max_f32_e32 v249, 1.0, v249
	v_max_f32_e32 v250, 1.0, v250
	v_cvt_f32_ubyte0_e32 v251, v199
	v_cvt_f32_ubyte1_e32 v252, v199
	v_cvt_f32_ubyte2_e32 v253, v199
	v_cvt_f32_ubyte3_e32 v254, v199
	v_rcp_f32_e32 v247, v247
	v_rcp_f32_e32 v248, v248
	v_rcp_f32_e32 v249, v249
	v_rcp_f32_e32 v250, v250
	v_mul_f32_e32 v251, v251, v247
	v_mul_f32_e32 v252, v252, v248
	v_mul_f32_e32 v253, v253, v249
	v_mul_f32_e32 v254, v254, v250
	v_mul_f32_e32 v52, v52, v251
	v_mul_f32_e32 v53, v53, v252
	v_mul_f32_e32 v54, v54, v253
	v_mul_f32_e32 v55, v55, v254
	s_waitcnt vmcnt(5)
	v_cvt_f32_ubyte0_e32 v247, v204
	v_cvt_f32_ubyte1_e32 v248, v204
	v_cvt_f32_ubyte2_e32 v249, v204
	v_cvt_f32_ubyte3_e32 v250, v204
	v_max_f32_e32 v247, 1.0, v247
	v_max_f32_e32 v248, 1.0, v248
	v_max_f32_e32 v249, 1.0, v249
	v_max_f32_e32 v250, 1.0, v250
	v_cvt_f32_ubyte0_e32 v251, v202
	v_cvt_f32_ubyte1_e32 v252, v202
	v_cvt_f32_ubyte2_e32 v253, v202
	v_cvt_f32_ubyte3_e32 v254, v202
	v_rcp_f32_e32 v247, v247
	v_rcp_f32_e32 v248, v248
	v_rcp_f32_e32 v249, v249
	v_rcp_f32_e32 v250, v250
	v_mul_f32_e32 v251, v251, v247
	v_mul_f32_e32 v252, v252, v248
	v_mul_f32_e32 v253, v253, v249
	v_mul_f32_e32 v254, v254, v250
	v_mul_f32_e32 v48, v48, v251
	v_mul_f32_e32 v49, v49, v252
	v_mul_f32_e32 v50, v50, v253
	v_mul_f32_e32 v51, v51, v254
	v_cvt_f32_ubyte0_e32 v247, v205
	v_cvt_f32_ubyte1_e32 v248, v205
	v_cvt_f32_ubyte2_e32 v249, v205
	v_cvt_f32_ubyte3_e32 v250, v205
	v_max_f32_e32 v247, 1.0, v247
	v_max_f32_e32 v248, 1.0, v248
	v_max_f32_e32 v249, 1.0, v249
	v_max_f32_e32 v250, 1.0, v250
	v_cvt_f32_ubyte0_e32 v251, v203
	v_cvt_f32_ubyte1_e32 v252, v203
	v_cvt_f32_ubyte2_e32 v253, v203
	v_cvt_f32_ubyte3_e32 v254, v203
	v_rcp_f32_e32 v247, v247
	v_rcp_f32_e32 v248, v248
	v_rcp_f32_e32 v249, v249
	v_rcp_f32_e32 v250, v250
	v_mul_f32_e32 v251, v251, v247
	v_mul_f32_e32 v252, v252, v248
	v_mul_f32_e32 v253, v253, v249
	v_mul_f32_e32 v254, v254, v250
	v_mul_f32_e32 v44, v44, v251
	v_mul_f32_e32 v45, v45, v252
	v_mul_f32_e32 v46, v46, v253
	v_mul_f32_e32 v47, v47, v254
	s_waitcnt vmcnt(4)
	v_cvt_f32_ubyte0_e32 v247, v208
	v_cvt_f32_ubyte1_e32 v248, v208
	v_cvt_f32_ubyte2_e32 v249, v208
	v_cvt_f32_ubyte3_e32 v250, v208
	v_max_f32_e32 v247, 1.0, v247
	v_max_f32_e32 v248, 1.0, v248
	v_max_f32_e32 v249, 1.0, v249
	v_max_f32_e32 v250, 1.0, v250
	v_cvt_f32_ubyte0_e32 v251, v206
	v_cvt_f32_ubyte1_e32 v252, v206
	v_cvt_f32_ubyte2_e32 v253, v206
	v_cvt_f32_ubyte3_e32 v254, v206
	v_rcp_f32_e32 v247, v247
	v_rcp_f32_e32 v248, v248
	v_rcp_f32_e32 v249, v249
	v_rcp_f32_e32 v250, v250
	v_mul_f32_e32 v251, v251, v247
	v_mul_f32_e32 v252, v252, v248
	v_mul_f32_e32 v253, v253, v249
	v_mul_f32_e32 v254, v254, v250
	v_mul_f32_e32 v40, v40, v251
	v_mul_f32_e32 v41, v41, v252
	v_mul_f32_e32 v42, v42, v253
	v_mul_f32_e32 v43, v43, v254
	v_cvt_f32_ubyte0_e32 v247, v209
	v_cvt_f32_ubyte1_e32 v248, v209
	v_cvt_f32_ubyte2_e32 v249, v209
	v_cvt_f32_ubyte3_e32 v250, v209
	v_max_f32_e32 v247, 1.0, v247
	v_max_f32_e32 v248, 1.0, v248
	v_max_f32_e32 v249, 1.0, v249
	v_max_f32_e32 v250, 1.0, v250
	v_cvt_f32_ubyte0_e32 v251, v207
	v_cvt_f32_ubyte1_e32 v252, v207
	v_cvt_f32_ubyte2_e32 v253, v207
	v_cvt_f32_ubyte3_e32 v254, v207
	v_rcp_f32_e32 v247, v247
	v_rcp_f32_e32 v248, v248
	v_rcp_f32_e32 v249, v249
	v_rcp_f32_e32 v250, v250
	v_mul_f32_e32 v251, v251, v247
	v_mul_f32_e32 v252, v252, v248
	v_mul_f32_e32 v253, v253, v249
	v_mul_f32_e32 v254, v254, v250
	v_mul_f32_e32 v36, v36, v251
	v_mul_f32_e32 v37, v37, v252
	v_mul_f32_e32 v38, v38, v253
	v_mul_f32_e32 v39, v39, v254
	s_waitcnt vmcnt(3)
	v_cvt_f32_ubyte0_e32 v247, v212
	v_cvt_f32_ubyte1_e32 v248, v212
	v_cvt_f32_ubyte2_e32 v249, v212
	v_cvt_f32_ubyte3_e32 v250, v212
	v_max_f32_e32 v247, 1.0, v247
	v_max_f32_e32 v248, 1.0, v248
	v_max_f32_e32 v249, 1.0, v249
	v_max_f32_e32 v250, 1.0, v250
	v_cvt_f32_ubyte0_e32 v251, v210
	v_cvt_f32_ubyte1_e32 v252, v210
	v_cvt_f32_ubyte2_e32 v253, v210
	v_cvt_f32_ubyte3_e32 v254, v210
	v_rcp_f32_e32 v247, v247
	v_rcp_f32_e32 v248, v248
	v_rcp_f32_e32 v249, v249
	v_rcp_f32_e32 v250, v250
	v_mul_f32_e32 v251, v251, v247
	v_mul_f32_e32 v252, v252, v248
	v_mul_f32_e32 v253, v253, v249
	v_mul_f32_e32 v254, v254, v250
	v_mul_f32_e32 v32, v32, v251
	v_mul_f32_e32 v33, v33, v252
	v_mul_f32_e32 v34, v34, v253
	v_mul_f32_e32 v35, v35, v254
	v_cvt_f32_ubyte0_e32 v247, v213
	v_cvt_f32_ubyte1_e32 v248, v213
	v_cvt_f32_ubyte2_e32 v249, v213
	v_cvt_f32_ubyte3_e32 v250, v213
	v_max_f32_e32 v247, 1.0, v247
	v_max_f32_e32 v248, 1.0, v248
	v_max_f32_e32 v249, 1.0, v249
	v_max_f32_e32 v250, 1.0, v250
	v_cvt_f32_ubyte0_e32 v251, v211
	v_cvt_f32_ubyte1_e32 v252, v211
	v_cvt_f32_ubyte2_e32 v253, v211
	v_cvt_f32_ubyte3_e32 v254, v211
	v_rcp_f32_e32 v247, v247
	v_rcp_f32_e32 v248, v248
	v_rcp_f32_e32 v249, v249
	v_rcp_f32_e32 v250, v250
	v_mul_f32_e32 v251, v251, v247
	v_mul_f32_e32 v252, v252, v248
	v_mul_f32_e32 v253, v253, v249
	v_mul_f32_e32 v254, v254, v250
	v_mul_f32_e32 v28, v28, v251
	v_mul_f32_e32 v29, v29, v252
	v_mul_f32_e32 v30, v30, v253
	v_mul_f32_e32 v31, v31, v254
	s_waitcnt vmcnt(2)
	v_cvt_f32_ubyte0_e32 v247, v218
	v_cvt_f32_ubyte1_e32 v248, v218
	v_cvt_f32_ubyte2_e32 v249, v218
	v_cvt_f32_ubyte3_e32 v250, v218
	v_max_f32_e32 v247, 1.0, v247
	v_max_f32_e32 v248, 1.0, v248
	v_max_f32_e32 v249, 1.0, v249
	v_max_f32_e32 v250, 1.0, v250
	v_cvt_f32_ubyte0_e32 v251, v216
	v_cvt_f32_ubyte1_e32 v252, v216
	v_cvt_f32_ubyte2_e32 v253, v216
	v_cvt_f32_ubyte3_e32 v254, v216
	v_rcp_f32_e32 v247, v247
	v_rcp_f32_e32 v248, v248
	v_rcp_f32_e32 v249, v249
	v_rcp_f32_e32 v250, v250
	v_mul_f32_e32 v251, v251, v247
	v_mul_f32_e32 v252, v252, v248
	v_mul_f32_e32 v253, v253, v249
	v_mul_f32_e32 v254, v254, v250
	v_mul_f32_e32 v24, v24, v251
	v_mul_f32_e32 v25, v25, v252
	v_mul_f32_e32 v26, v26, v253
	v_mul_f32_e32 v27, v27, v254
	v_cvt_f32_ubyte0_e32 v247, v219
	v_cvt_f32_ubyte1_e32 v248, v219
	v_cvt_f32_ubyte2_e32 v249, v219
	v_cvt_f32_ubyte3_e32 v250, v219
	v_max_f32_e32 v247, 1.0, v247
	v_max_f32_e32 v248, 1.0, v248
	v_max_f32_e32 v249, 1.0, v249
	v_max_f32_e32 v250, 1.0, v250
	v_cvt_f32_ubyte0_e32 v251, v217
	v_cvt_f32_ubyte1_e32 v252, v217
	v_cvt_f32_ubyte2_e32 v253, v217
	v_cvt_f32_ubyte3_e32 v254, v217
	v_rcp_f32_e32 v247, v247
	v_rcp_f32_e32 v248, v248
	v_rcp_f32_e32 v249, v249
	v_rcp_f32_e32 v250, v250
	v_mul_f32_e32 v251, v251, v247
	v_mul_f32_e32 v252, v252, v248
	v_mul_f32_e32 v253, v253, v249
	v_mul_f32_e32 v254, v254, v250
	v_mul_f32_e32 v20, v20, v251
	v_mul_f32_e32 v21, v21, v252
	v_mul_f32_e32 v22, v22, v253
	v_mul_f32_e32 v23, v23, v254
	s_waitcnt vmcnt(1)
	v_cvt_f32_ubyte0_e32 v247, v222
	v_cvt_f32_ubyte1_e32 v248, v222
	v_cvt_f32_ubyte2_e32 v249, v222
	v_cvt_f32_ubyte3_e32 v250, v222
	v_max_f32_e32 v247, 1.0, v247
	v_max_f32_e32 v248, 1.0, v248
	v_max_f32_e32 v249, 1.0, v249
	v_max_f32_e32 v250, 1.0, v250
	v_cvt_f32_ubyte0_e32 v251, v220
	v_cvt_f32_ubyte1_e32 v252, v220
	v_cvt_f32_ubyte2_e32 v253, v220
	v_cvt_f32_ubyte3_e32 v254, v220
	v_rcp_f32_e32 v247, v247
	v_rcp_f32_e32 v248, v248
	v_rcp_f32_e32 v249, v249
	v_rcp_f32_e32 v250, v250
	v_mul_f32_e32 v251, v251, v247
	v_mul_f32_e32 v252, v252, v248
	v_mul_f32_e32 v253, v253, v249
	v_mul_f32_e32 v254, v254, v250
	v_mul_f32_e32 v16, v16, v251
	v_mul_f32_e32 v17, v17, v252
	v_mul_f32_e32 v18, v18, v253
	v_mul_f32_e32 v19, v19, v254
	v_cvt_f32_ubyte0_e32 v247, v223
	v_cvt_f32_ubyte1_e32 v248, v223
	v_cvt_f32_ubyte2_e32 v249, v223
	v_cvt_f32_ubyte3_e32 v250, v223
	v_max_f32_e32 v247, 1.0, v247
	v_max_f32_e32 v248, 1.0, v248
	v_max_f32_e32 v249, 1.0, v249
	v_max_f32_e32 v250, 1.0, v250
	v_cvt_f32_ubyte0_e32 v251, v221
	v_cvt_f32_ubyte1_e32 v252, v221
	v_cvt_f32_ubyte2_e32 v253, v221
	v_cvt_f32_ubyte3_e32 v254, v221
	v_rcp_f32_e32 v247, v247
	v_rcp_f32_e32 v248, v248
	v_rcp_f32_e32 v249, v249
	v_rcp_f32_e32 v250, v250
	v_mul_f32_e32 v251, v251, v247
	v_mul_f32_e32 v252, v252, v248
	v_mul_f32_e32 v253, v253, v249
	v_mul_f32_e32 v254, v254, v250
	v_mul_f32_e32 v12, v12, v251
	v_mul_f32_e32 v13, v13, v252
	v_mul_f32_e32 v14, v14, v253
	v_mul_f32_e32 v15, v15, v254
	s_waitcnt vmcnt(0)
	v_cvt_f32_ubyte0_e32 v247, v226
	v_cvt_f32_ubyte1_e32 v248, v226
	v_cvt_f32_ubyte2_e32 v249, v226
	v_cvt_f32_ubyte3_e32 v250, v226
	v_max_f32_e32 v247, 1.0, v247
	v_max_f32_e32 v248, 1.0, v248
	v_max_f32_e32 v249, 1.0, v249
	v_max_f32_e32 v250, 1.0, v250
	v_cvt_f32_ubyte0_e32 v251, v224
	v_cvt_f32_ubyte1_e32 v252, v224
	v_cvt_f32_ubyte2_e32 v253, v224
	v_cvt_f32_ubyte3_e32 v254, v224
	v_rcp_f32_e32 v247, v247
	v_rcp_f32_e32 v248, v248
	v_rcp_f32_e32 v249, v249
	v_rcp_f32_e32 v250, v250
	v_mul_f32_e32 v251, v251, v247
	v_mul_f32_e32 v252, v252, v248
	v_mul_f32_e32 v253, v253, v249
	v_mul_f32_e32 v254, v254, v250
	v_mul_f32_e32 v8, v8, v251
	v_mul_f32_e32 v9, v9, v252
	v_mul_f32_e32 v10, v10, v253
	v_mul_f32_e32 v11, v11, v254
	v_cvt_f32_ubyte0_e32 v247, v227
	v_cvt_f32_ubyte1_e32 v248, v227
	v_cvt_f32_ubyte2_e32 v249, v227
	v_cvt_f32_ubyte3_e32 v250, v227
	v_max_f32_e32 v247, 1.0, v247
	v_max_f32_e32 v248, 1.0, v248
	v_max_f32_e32 v249, 1.0, v249
	v_max_f32_e32 v250, 1.0, v250
	v_cvt_f32_ubyte0_e32 v251, v225
	v_cvt_f32_ubyte1_e32 v252, v225
	v_cvt_f32_ubyte2_e32 v253, v225
	v_cvt_f32_ubyte3_e32 v254, v225
	v_rcp_f32_e32 v247, v247
	v_rcp_f32_e32 v248, v248
	v_rcp_f32_e32 v249, v249
	v_rcp_f32_e32 v250, v250
	v_mul_f32_e32 v251, v251, v247
	v_mul_f32_e32 v252, v252, v248
	v_mul_f32_e32 v253, v253, v249
	v_mul_f32_e32 v254, v254, v250
	v_mul_f32_e32 v4, v4, v251
	v_mul_f32_e32 v5, v5, v252
	v_mul_f32_e32 v6, v6, v253
	v_mul_f32_e32 v7, v7, v254
	s_andn2_b64 vcc, exec, s[4:5]
	s_cbranch_vccnz .Lp3mid_b
	s_barrier
.Lp3mid_b:
	s_branch .LBB0_812

.LBB0_817:
	v_mov_b32_e32 v2, v164
	v_mad_i64_i32 v[2:3], s[2:3], v2, s42, v[166:167]
	global_load_dwordx2 v[178:179], v[2:3], off offset:8
	global_load_dwordx2 v[180:181], v[2:3], off offset:264
	v_add_u32_e32 v2, 16, v164
	v_mad_i64_i32 v[2:3], s[2:3], v2, s42, v[166:167]
	global_load_dwordx2 v[182:183], v[2:3], off offset:8
	global_load_dwordx2 v[184:185], v[2:3], off offset:264
	v_add_u32_e32 v2, 32, v164
	v_mad_i64_i32 v[2:3], s[2:3], v2, s42, v[166:167]
	global_load_dwordx2 v[186:187], v[2:3], off offset:8
	global_load_dwordx2 v[188:189], v[2:3], off offset:264
	v_add_u32_e32 v2, 48, v164
	v_mad_i64_i32 v[2:3], s[2:3], v2, s42, v[166:167]
	global_load_dwordx2 v[190:191], v[2:3], off offset:8
	global_load_dwordx2 v[192:193], v[2:3], off offset:264
	v_add_u32_e32 v2, 0x80, v164
	v_mad_i64_i32 v[2:3], s[2:3], v2, s42, v[166:167]
	global_load_dwordx2 v[194:195], v[2:3], off offset:8
	global_load_dwordx2 v[196:197], v[2:3], off offset:264
	v_add_u32_e32 v2, 0x90, v164
	v_mad_i64_i32 v[2:3], s[2:3], v2, s42, v[166:167]
	global_load_dwordx2 v[198:199], v[2:3], off offset:8
	global_load_dwordx2 v[200:201], v[2:3], off offset:264
	v_add_u32_e32 v2, 0xa0, v164
	v_mad_i64_i32 v[2:3], s[2:3], v2, s42, v[166:167]
	global_load_dwordx2 v[202:203], v[2:3], off offset:8
	global_load_dwordx2 v[204:205], v[2:3], off offset:264
	v_add_u32_e32 v2, 0xb0, v164
	v_mad_i64_i32 v[2:3], s[2:3], v2, s42, v[166:167]
	global_load_dwordx2 v[206:207], v[2:3], off offset:8
	global_load_dwordx2 v[208:209], v[2:3], off offset:264
	v_lshl_or_b32 v2, s45, 8, v174
	v_mov_b64_e32 v[134:135], s[8:9]
	v_lshlrev_b32_e32 v132, 1, v2
	v_mad_i64_i32 v[136:137], s[2:3], v164, s42, v[134:135]
	v_ashrrev_i32_e32 v133, 31, v132
	v_lshl_add_u64 v[136:137], v[136:137], 0, v[132:133]
	v_ashrrev_i32_e32 v165, 31, v164
	s_andn2_b64 vcc, exec, s[6:7]
	s_waitcnt vmcnt(15)
	v_mov_b32_e32 v138, v178
	v_mov_b32_e32 v139, v179
	v_cvt_f32_ubyte0_e32 v1, v138
	v_cvt_f32_ubyte0_e32 v3, v139
	v_cvt_f32_ubyte1_e32 v140, v138
	v_cvt_f32_ubyte1_e32 v141, v139
	v_cvt_f32_ubyte2_e32 v142, v138
	v_cvt_f32_ubyte2_e32 v143, v139
	v_cvt_f32_ubyte3_e32 v139, v139
	v_cvt_f32_ubyte3_e32 v138, v138
	v_max_f32_e32 v1, 1.0, v1
	v_max_f32_e32 v140, 1.0, v140
	v_max_f32_e32 v142, 1.0, v142
	v_max_f32_e32 v139, 1.0, v139
	v_max_f32_e32 v3, 1.0, v3
	v_max_f32_e32 v141, 1.0, v141
	v_max_f32_e32 v143, 1.0, v143
	v_max_f32_e32 v138, 1.0, v138
	v_mul_f32_e32 v1, 0x3b808081, v1
	v_mul_f32_e32 v140, 0x3b808081, v140
	v_mul_f32_e32 v142, 0x3b808081, v142
	v_mul_f32_e32 v139, 0x3b808081, v139
	v_mul_f32_e32 v3, 0x3b808081, v3
	v_mul_f32_e32 v141, 0x3b808081, v141
	v_mul_f32_e32 v143, 0x3b808081, v143
	v_mul_f32_e32 v138, 0x3b808081, v138
	v_mul_f32_e32 v1, v128, v1
	v_mul_f32_e32 v128, v129, v140
	v_mul_f32_e32 v129, v130, v142
	v_mul_f32_e32 v127, v127, v139
	v_mul_f32_e32 v130, v131, v138
	v_mul_f32_e32 v3, v124, v3
	v_mul_f32_e32 v131, v125, v141
	v_mul_f32_e32 v138, v126, v143
	v_cvt_pk_bf16_f32 v124, v1, v128
	v_cvt_pk_bf16_f32 v125, v129, v130
	v_cvt_pk_bf16_f32 v126, v3, v131
	v_cvt_pk_bf16_f32 v127, v138, v127
	v_ashrrev_i32_e32 v3, 31, v2
	v_lshlrev_b64 v[136:137], 11, v[164:165]
	v_lshl_add_u64 v[136:137], s[88:89], 0, v[136:137]
	v_lshlrev_b64 v[2:3], 1, v[2:3]
	v_lshl_add_u64 v[136:137], v[136:137], 0, v[2:3]
	global_store_dwordx4 v[136:137], v[124:127], off
	v_or_b32_e32 v130, 16, v164
	v_mad_i64_i32 v[138:139], s[2:3], v130, s42, v[134:135]
	v_lshl_add_u64 v[138:139], v[138:139], 0, v[132:133]
	s_waitcnt vmcnt(15)
	v_mov_b32_e32 v128, v180
	v_mov_b32_e32 v129, v181
	v_cvt_f32_ubyte0_e32 v1, v128
	v_cvt_f32_ubyte0_e32 v124, v129
	v_cvt_f32_ubyte1_e32 v125, v128
	v_cvt_f32_ubyte1_e32 v126, v129
	v_cvt_f32_ubyte2_e32 v127, v128
	v_cvt_f32_ubyte2_e32 v131, v129
	v_cvt_f32_ubyte3_e32 v129, v129
	v_cvt_f32_ubyte3_e32 v128, v128
	v_max_f32_e32 v1, 1.0, v1
	v_max_f32_e32 v125, 1.0, v125
	v_max_f32_e32 v127, 1.0, v127
	v_max_f32_e32 v129, 1.0, v129
	v_max_f32_e32 v124, 1.0, v124
	v_max_f32_e32 v126, 1.0, v126
	v_max_f32_e32 v131, 1.0, v131
	v_max_f32_e32 v128, 1.0, v128
	v_mul_f32_e32 v1, 0x3b808081, v1
	v_mul_f32_e32 v125, 0x3b808081, v125
	v_mul_f32_e32 v127, 0x3b808081, v127
	v_mul_f32_e32 v129, 0x3b808081, v129
	v_mul_f32_e32 v124, 0x3b808081, v124
	v_mul_f32_e32 v126, 0x3b808081, v126
	v_mul_f32_e32 v131, 0x3b808081, v131
	v_mul_f32_e32 v128, 0x3b808081, v128
	v_mul_f32_e32 v1, v120, v1
	v_mul_f32_e32 v120, v121, v125
	v_mul_f32_e32 v121, v122, v127
	v_mul_f32_e32 v119, v119, v129
	v_mul_f32_e32 v122, v123, v128
	v_mul_f32_e32 v123, v116, v124
	v_mul_f32_e32 v124, v117, v126
	v_mul_f32_e32 v125, v118, v131
	v_cvt_pk_bf16_f32 v116, v1, v120
	v_cvt_pk_bf16_f32 v117, v121, v122
	v_cvt_pk_bf16_f32 v118, v123, v124
	v_cvt_pk_bf16_f32 v119, v125, v119
	v_ashrrev_i32_e32 v131, 31, v130
	global_store_dwordx4 v[136:137], v[116:119], off offset:256
	s_waitcnt vmcnt(15)
	v_mov_b32_e32 v120, v182
	v_mov_b32_e32 v121, v183
	v_cvt_f32_ubyte0_e32 v1, v120
	v_cvt_f32_ubyte0_e32 v116, v121
	v_cvt_f32_ubyte1_e32 v117, v120
	v_cvt_f32_ubyte1_e32 v118, v121
	v_cvt_f32_ubyte2_e32 v119, v120
	v_cvt_f32_ubyte2_e32 v122, v121
	v_cvt_f32_ubyte3_e32 v121, v121
	v_cvt_f32_ubyte3_e32 v120, v120
	v_max_f32_e32 v1, 1.0, v1
	v_max_f32_e32 v117, 1.0, v117
	v_max_f32_e32 v119, 1.0, v119
	v_max_f32_e32 v121, 1.0, v121
	v_max_f32_e32 v116, 1.0, v116
	v_max_f32_e32 v118, 1.0, v118
	v_max_f32_e32 v122, 1.0, v122
	v_max_f32_e32 v120, 1.0, v120
	v_mul_f32_e32 v1, 0x3b808081, v1
	v_mul_f32_e32 v117, 0x3b808081, v117
	v_mul_f32_e32 v119, 0x3b808081, v119
	v_mul_f32_e32 v121, 0x3b808081, v121
	v_mul_f32_e32 v116, 0x3b808081, v116
	v_mul_f32_e32 v118, 0x3b808081, v118
	v_mul_f32_e32 v122, 0x3b808081, v122
	v_mul_f32_e32 v120, 0x3b808081, v120
	v_mul_f32_e32 v1, v112, v1
	v_mul_f32_e32 v112, v113, v117
	v_mul_f32_e32 v113, v114, v119
	v_mul_f32_e32 v111, v111, v121
	v_mul_f32_e32 v114, v115, v120
	v_mul_f32_e32 v115, v108, v116
	v_mul_f32_e32 v116, v109, v118
	v_mul_f32_e32 v117, v110, v122
	v_cvt_pk_bf16_f32 v108, v1, v112
	v_cvt_pk_bf16_f32 v109, v113, v114
	v_cvt_pk_bf16_f32 v110, v115, v116
	v_cvt_pk_bf16_f32 v111, v117, v111
	v_lshlrev_b64 v[118:119], 11, v[130:131]
	v_lshl_add_u64 v[118:119], s[88:89], 0, v[118:119]
	v_lshl_add_u64 v[118:119], v[118:119], 0, v[2:3]
	global_store_dwordx4 v[118:119], v[108:111], off
	v_or_b32_e32 v114, 32, v164
	v_mad_i64_i32 v[116:117], s[2:3], v114, s42, v[134:135]
	v_lshl_add_u64 v[116:117], v[116:117], 0, v[132:133]
	s_waitcnt vmcnt(15)
	v_mov_b32_e32 v112, v184
	v_mov_b32_e32 v113, v185
	v_cvt_f32_ubyte0_e32 v1, v112
	v_cvt_f32_ubyte0_e32 v108, v113
	v_cvt_f32_ubyte1_e32 v109, v112
	v_cvt_f32_ubyte1_e32 v110, v113
	v_cvt_f32_ubyte2_e32 v111, v112
	v_cvt_f32_ubyte2_e32 v115, v113
	v_cvt_f32_ubyte3_e32 v113, v113
	v_cvt_f32_ubyte3_e32 v112, v112
	v_max_f32_e32 v1, 1.0, v1
	v_max_f32_e32 v109, 1.0, v109
	v_max_f32_e32 v111, 1.0, v111
	v_max_f32_e32 v113, 1.0, v113
	v_max_f32_e32 v108, 1.0, v108
	v_max_f32_e32 v110, 1.0, v110
	v_max_f32_e32 v115, 1.0, v115
	v_max_f32_e32 v112, 1.0, v112
	v_mul_f32_e32 v1, 0x3b808081, v1
	v_mul_f32_e32 v109, 0x3b808081, v109
	v_mul_f32_e32 v111, 0x3b808081, v111
	v_mul_f32_e32 v113, 0x3b808081, v113
	v_mul_f32_e32 v108, 0x3b808081, v108
	v_mul_f32_e32 v110, 0x3b808081, v110
	v_mul_f32_e32 v115, 0x3b808081, v115
	v_mul_f32_e32 v112, 0x3b808081, v112
	v_mul_f32_e32 v1, v104, v1
	v_mul_f32_e32 v104, v105, v109
	v_mul_f32_e32 v105, v106, v111
	v_mul_f32_e32 v103, v103, v113
	v_mul_f32_e32 v106, v107, v112
	v_mul_f32_e32 v107, v100, v108
	v_mul_f32_e32 v108, v101, v110
	v_mul_f32_e32 v109, v102, v115
	v_cvt_pk_bf16_f32 v100, v1, v104
	v_cvt_pk_bf16_f32 v101, v105, v106
	v_cvt_pk_bf16_f32 v102, v107, v108
	v_cvt_pk_bf16_f32 v103, v109, v103
	v_ashrrev_i32_e32 v115, 31, v114
	global_store_dwordx4 v[118:119], v[100:103], off offset:256
	s_waitcnt vmcnt(15)
	v_mov_b32_e32 v104, v186
	v_mov_b32_e32 v105, v187
	v_cvt_f32_ubyte0_e32 v1, v104
	v_cvt_f32_ubyte0_e32 v100, v105
	v_cvt_f32_ubyte1_e32 v101, v104
	v_cvt_f32_ubyte1_e32 v102, v105
	v_cvt_f32_ubyte2_e32 v103, v104
	v_cvt_f32_ubyte2_e32 v106, v105
	v_cvt_f32_ubyte3_e32 v105, v105
	v_cvt_f32_ubyte3_e32 v104, v104
	v_max_f32_e32 v1, 1.0, v1
	v_max_f32_e32 v101, 1.0, v101
	v_max_f32_e32 v103, 1.0, v103
	v_max_f32_e32 v105, 1.0, v105
	v_max_f32_e32 v100, 1.0, v100
	v_max_f32_e32 v102, 1.0, v102
	v_max_f32_e32 v106, 1.0, v106
	v_max_f32_e32 v104, 1.0, v104
	v_mul_f32_e32 v1, 0x3b808081, v1
	v_mul_f32_e32 v101, 0x3b808081, v101
	v_mul_f32_e32 v103, 0x3b808081, v103
	v_mul_f32_e32 v105, 0x3b808081, v105
	v_mul_f32_e32 v100, 0x3b808081, v100
	v_mul_f32_e32 v102, 0x3b808081, v102
	v_mul_f32_e32 v106, 0x3b808081, v106
	v_mul_f32_e32 v104, 0x3b808081, v104
	v_mul_f32_e32 v1, v96, v1
	v_mul_f32_e32 v96, v97, v101
	v_mul_f32_e32 v97, v98, v103
	v_mul_f32_e32 v95, v95, v105
	v_mul_f32_e32 v98, v99, v104
	v_mul_f32_e32 v99, v92, v100
	v_mul_f32_e32 v100, v93, v102
	v_mul_f32_e32 v101, v94, v106
	v_cvt_pk_bf16_f32 v92, v1, v96
	v_cvt_pk_bf16_f32 v93, v97, v98
	v_cvt_pk_bf16_f32 v94, v99, v100
	v_cvt_pk_bf16_f32 v95, v101, v95
	v_lshlrev_b64 v[102:103], 11, v[114:115]
	v_lshl_add_u64 v[102:103], s[88:89], 0, v[102:103]
	v_lshl_add_u64 v[102:103], v[102:103], 0, v[2:3]
	global_store_dwordx4 v[102:103], v[92:95], off
	v_or_b32_e32 v98, 48, v164
	v_mad_i64_i32 v[100:101], s[2:3], v98, s42, v[134:135]
	v_lshl_add_u64 v[100:101], v[100:101], 0, v[132:133]
	s_waitcnt vmcnt(15)
	v_mov_b32_e32 v96, v188
	v_mov_b32_e32 v97, v189
	v_cvt_f32_ubyte0_e32 v1, v96
	v_cvt_f32_ubyte0_e32 v92, v97
	v_cvt_f32_ubyte1_e32 v93, v96
	v_cvt_f32_ubyte1_e32 v94, v97
	v_cvt_f32_ubyte2_e32 v95, v96
	v_cvt_f32_ubyte2_e32 v99, v97
	v_cvt_f32_ubyte3_e32 v97, v97
	v_cvt_f32_ubyte3_e32 v96, v96
	v_max_f32_e32 v1, 1.0, v1
	v_max_f32_e32 v93, 1.0, v93
	v_max_f32_e32 v95, 1.0, v95
	v_max_f32_e32 v97, 1.0, v97
	v_max_f32_e32 v92, 1.0, v92
	v_max_f32_e32 v94, 1.0, v94
	v_max_f32_e32 v99, 1.0, v99
	v_max_f32_e32 v96, 1.0, v96
	v_mul_f32_e32 v1, 0x3b808081, v1
	v_mul_f32_e32 v93, 0x3b808081, v93
	v_mul_f32_e32 v95, 0x3b808081, v95
	v_mul_f32_e32 v97, 0x3b808081, v97
	v_mul_f32_e32 v92, 0x3b808081, v92
	v_mul_f32_e32 v94, 0x3b808081, v94
	v_mul_f32_e32 v99, 0x3b808081, v99
	v_mul_f32_e32 v96, 0x3b808081, v96
	v_mul_f32_e32 v1, v88, v1
	v_mul_f32_e32 v88, v89, v93
	v_mul_f32_e32 v89, v90, v95
	v_mul_f32_e32 v87, v87, v97
	v_mul_f32_e32 v90, v91, v96
	v_mul_f32_e32 v91, v84, v92
	v_mul_f32_e32 v92, v85, v94
	v_mul_f32_e32 v93, v86, v99
	v_cvt_pk_bf16_f32 v84, v1, v88
	v_cvt_pk_bf16_f32 v85, v89, v90
	v_cvt_pk_bf16_f32 v86, v91, v92
	v_cvt_pk_bf16_f32 v87, v93, v87
	v_ashrrev_i32_e32 v99, 31, v98
	global_store_dwordx4 v[102:103], v[84:87], off offset:256
	s_waitcnt vmcnt(15)
	v_mov_b32_e32 v88, v190
	v_mov_b32_e32 v89, v191
	v_cvt_f32_ubyte0_e32 v1, v88
	v_cvt_f32_ubyte0_e32 v84, v89
	v_cvt_f32_ubyte1_e32 v85, v88
	v_cvt_f32_ubyte1_e32 v86, v89
	v_cvt_f32_ubyte2_e32 v87, v88
	v_cvt_f32_ubyte2_e32 v90, v89
	v_cvt_f32_ubyte3_e32 v89, v89
	v_cvt_f32_ubyte3_e32 v88, v88
	v_max_f32_e32 v1, 1.0, v1
	v_max_f32_e32 v85, 1.0, v85
	v_max_f32_e32 v87, 1.0, v87
	v_max_f32_e32 v89, 1.0, v89
	v_max_f32_e32 v84, 1.0, v84
	v_max_f32_e32 v86, 1.0, v86
	v_max_f32_e32 v90, 1.0, v90
	v_max_f32_e32 v88, 1.0, v88
	v_mul_f32_e32 v1, 0x3b808081, v1
	v_mul_f32_e32 v85, 0x3b808081, v85
	v_mul_f32_e32 v87, 0x3b808081, v87
	v_mul_f32_e32 v89, 0x3b808081, v89
	v_mul_f32_e32 v84, 0x3b808081, v84
	v_mul_f32_e32 v86, 0x3b808081, v86
	v_mul_f32_e32 v90, 0x3b808081, v90
	v_mul_f32_e32 v88, 0x3b808081, v88
	v_mul_f32_e32 v1, v80, v1
	v_mul_f32_e32 v80, v81, v85
	v_mul_f32_e32 v81, v82, v87
	v_mul_f32_e32 v79, v79, v89
	v_mul_f32_e32 v82, v83, v88
	v_mul_f32_e32 v83, v76, v84
	v_mul_f32_e32 v84, v77, v86
	v_mul_f32_e32 v85, v78, v90
	v_cvt_pk_bf16_f32 v76, v1, v80
	v_cvt_pk_bf16_f32 v77, v81, v82
	v_cvt_pk_bf16_f32 v78, v83, v84
	v_cvt_pk_bf16_f32 v79, v85, v79
	v_lshlrev_b64 v[86:87], 11, v[98:99]
	v_lshl_add_u64 v[86:87], s[88:89], 0, v[86:87]
	v_lshl_add_u64 v[86:87], v[86:87], 0, v[2:3]
	global_store_dwordx4 v[86:87], v[76:79], off
	v_add_u32_e32 v82, 0x80, v164
	v_mad_i64_i32 v[84:85], s[2:3], v82, s42, v[134:135]
	v_lshl_add_u64 v[84:85], v[84:85], 0, v[132:133]
	s_waitcnt vmcnt(15)
	v_mov_b32_e32 v80, v192
	v_mov_b32_e32 v81, v193
	v_cvt_f32_ubyte0_e32 v1, v80
	v_cvt_f32_ubyte0_e32 v76, v81
	v_cvt_f32_ubyte1_e32 v77, v80
	v_cvt_f32_ubyte1_e32 v78, v81
	v_cvt_f32_ubyte2_e32 v79, v80
	v_cvt_f32_ubyte2_e32 v83, v81
	v_cvt_f32_ubyte3_e32 v81, v81
	v_cvt_f32_ubyte3_e32 v80, v80
	v_max_f32_e32 v1, 1.0, v1
	v_max_f32_e32 v77, 1.0, v77
	v_max_f32_e32 v79, 1.0, v79
	v_max_f32_e32 v81, 1.0, v81
	v_max_f32_e32 v76, 1.0, v76
	v_max_f32_e32 v78, 1.0, v78
	v_max_f32_e32 v83, 1.0, v83
	v_max_f32_e32 v80, 1.0, v80
	v_mul_f32_e32 v1, 0x3b808081, v1
	v_mul_f32_e32 v77, 0x3b808081, v77
	v_mul_f32_e32 v79, 0x3b808081, v79
	v_mul_f32_e32 v81, 0x3b808081, v81
	v_mul_f32_e32 v76, 0x3b808081, v76
	v_mul_f32_e32 v78, 0x3b808081, v78
	v_mul_f32_e32 v83, 0x3b808081, v83
	v_mul_f32_e32 v80, 0x3b808081, v80
	v_mul_f32_e32 v1, v72, v1
	v_mul_f32_e32 v72, v73, v77
	v_mul_f32_e32 v73, v74, v79
	v_mul_f32_e32 v71, v71, v81
	v_mul_f32_e32 v74, v75, v80
	v_mul_f32_e32 v75, v68, v76
	v_mul_f32_e32 v76, v69, v78
	v_mul_f32_e32 v77, v70, v83
	v_cvt_pk_bf16_f32 v68, v1, v72
	v_cvt_pk_bf16_f32 v69, v73, v74
	v_cvt_pk_bf16_f32 v70, v75, v76
	v_cvt_pk_bf16_f32 v71, v77, v71
	v_ashrrev_i32_e32 v83, 31, v82
	global_store_dwordx4 v[86:87], v[68:71], off offset:256
	s_waitcnt vmcnt(15)
	v_mov_b32_e32 v72, v194
	v_mov_b32_e32 v73, v195
	v_cvt_f32_ubyte0_e32 v1, v72
	v_cvt_f32_ubyte0_e32 v68, v73
	v_cvt_f32_ubyte1_e32 v69, v72
	v_cvt_f32_ubyte1_e32 v70, v73
	v_cvt_f32_ubyte2_e32 v71, v72
	v_cvt_f32_ubyte2_e32 v74, v73
	v_cvt_f32_ubyte3_e32 v73, v73
	v_cvt_f32_ubyte3_e32 v72, v72
	v_max_f32_e32 v1, 1.0, v1
	v_max_f32_e32 v69, 1.0, v69
	v_max_f32_e32 v71, 1.0, v71
	v_max_f32_e32 v73, 1.0, v73
	v_max_f32_e32 v68, 1.0, v68
	v_max_f32_e32 v70, 1.0, v70
	v_max_f32_e32 v74, 1.0, v74
	v_max_f32_e32 v72, 1.0, v72
	v_mul_f32_e32 v1, 0x3b808081, v1
	v_mul_f32_e32 v69, 0x3b808081, v69
	v_mul_f32_e32 v71, 0x3b808081, v71
	v_mul_f32_e32 v73, 0x3b808081, v73
	v_mul_f32_e32 v68, 0x3b808081, v68
	v_mul_f32_e32 v70, 0x3b808081, v70
	v_mul_f32_e32 v74, 0x3b808081, v74
	v_mul_f32_e32 v72, 0x3b808081, v72
	v_mul_f32_e32 v1, v64, v1
	v_mul_f32_e32 v64, v65, v69
	v_mul_f32_e32 v65, v66, v71
	v_mul_f32_e32 v63, v63, v73
	v_mul_f32_e32 v66, v67, v72
	v_mul_f32_e32 v67, v60, v68
	v_mul_f32_e32 v68, v61, v70
	v_mul_f32_e32 v69, v62, v74
	v_cvt_pk_bf16_f32 v60, v1, v64
	v_cvt_pk_bf16_f32 v61, v65, v66
	v_cvt_pk_bf16_f32 v62, v67, v68
	v_cvt_pk_bf16_f32 v63, v69, v63
	v_lshlrev_b64 v[70:71], 11, v[82:83]
	v_lshl_add_u64 v[70:71], s[88:89], 0, v[70:71]
	v_lshl_add_u64 v[70:71], v[70:71], 0, v[2:3]
	global_store_dwordx4 v[70:71], v[60:63], off
	v_add_u32_e32 v66, 0x90, v164
	v_mad_i64_i32 v[68:69], s[2:3], v66, s42, v[134:135]
	v_lshl_add_u64 v[68:69], v[68:69], 0, v[132:133]
	s_waitcnt vmcnt(15)
	v_mov_b32_e32 v64, v196
	v_mov_b32_e32 v65, v197
	v_cvt_f32_ubyte0_e32 v1, v64
	v_cvt_f32_ubyte0_e32 v60, v65
	v_cvt_f32_ubyte1_e32 v61, v64
	v_cvt_f32_ubyte1_e32 v62, v65
	v_cvt_f32_ubyte2_e32 v63, v64
	v_cvt_f32_ubyte2_e32 v67, v65
	v_cvt_f32_ubyte3_e32 v65, v65
	v_cvt_f32_ubyte3_e32 v64, v64
	v_max_f32_e32 v1, 1.0, v1
	v_max_f32_e32 v61, 1.0, v61
	v_max_f32_e32 v63, 1.0, v63
	v_max_f32_e32 v65, 1.0, v65
	v_max_f32_e32 v60, 1.0, v60
	v_max_f32_e32 v62, 1.0, v62
	v_max_f32_e32 v67, 1.0, v67
	v_max_f32_e32 v64, 1.0, v64
	v_mul_f32_e32 v1, 0x3b808081, v1
	v_mul_f32_e32 v61, 0x3b808081, v61
	v_mul_f32_e32 v63, 0x3b808081, v63
	v_mul_f32_e32 v65, 0x3b808081, v65
	v_mul_f32_e32 v60, 0x3b808081, v60
	v_mul_f32_e32 v62, 0x3b808081, v62
	v_mul_f32_e32 v67, 0x3b808081, v67
	v_mul_f32_e32 v64, 0x3b808081, v64
	v_mul_f32_e32 v1, v56, v1
	v_mul_f32_e32 v56, v57, v61
	v_mul_f32_e32 v57, v58, v63
	v_mul_f32_e32 v55, v55, v65
	v_mul_f32_e32 v58, v59, v64
	v_mul_f32_e32 v59, v52, v60
	v_mul_f32_e32 v60, v53, v62
	v_mul_f32_e32 v61, v54, v67
	v_cvt_pk_bf16_f32 v52, v1, v56
	v_cvt_pk_bf16_f32 v53, v57, v58
	v_cvt_pk_bf16_f32 v54, v59, v60
	v_cvt_pk_bf16_f32 v55, v61, v55
	v_ashrrev_i32_e32 v67, 31, v66
	global_store_dwordx4 v[70:71], v[52:55], off offset:256
	s_waitcnt vmcnt(15)
	v_mov_b32_e32 v56, v198
	v_mov_b32_e32 v57, v199
	v_cvt_f32_ubyte0_e32 v1, v56
	v_cvt_f32_ubyte0_e32 v52, v57
	v_cvt_f32_ubyte1_e32 v53, v56
	v_cvt_f32_ubyte1_e32 v54, v57
	v_cvt_f32_ubyte2_e32 v55, v56
	v_cvt_f32_ubyte2_e32 v58, v57
	v_cvt_f32_ubyte3_e32 v57, v57
	v_cvt_f32_ubyte3_e32 v56, v56
	v_max_f32_e32 v1, 1.0, v1
	v_max_f32_e32 v53, 1.0, v53
	v_max_f32_e32 v55, 1.0, v55
	v_max_f32_e32 v57, 1.0, v57
	v_max_f32_e32 v52, 1.0, v52
	v_max_f32_e32 v54, 1.0, v54
	v_max_f32_e32 v58, 1.0, v58
	v_max_f32_e32 v56, 1.0, v56
	v_mul_f32_e32 v1, 0x3b808081, v1
	v_mul_f32_e32 v53, 0x3b808081, v53
	v_mul_f32_e32 v55, 0x3b808081, v55
	v_mul_f32_e32 v57, 0x3b808081, v57
	v_mul_f32_e32 v52, 0x3b808081, v52
	v_mul_f32_e32 v54, 0x3b808081, v54
	v_mul_f32_e32 v58, 0x3b808081, v58
	v_mul_f32_e32 v56, 0x3b808081, v56
	v_mul_f32_e32 v1, v48, v1
	v_mul_f32_e32 v48, v49, v53
	v_mul_f32_e32 v49, v50, v55
	v_mul_f32_e32 v47, v47, v57
	v_mul_f32_e32 v50, v51, v56
	v_mul_f32_e32 v51, v44, v52
	v_mul_f32_e32 v52, v45, v54
	v_mul_f32_e32 v53, v46, v58
	v_cvt_pk_bf16_f32 v44, v1, v48
	v_cvt_pk_bf16_f32 v45, v49, v50
	v_cvt_pk_bf16_f32 v46, v51, v52
	v_cvt_pk_bf16_f32 v47, v53, v47
	v_lshlrev_b64 v[54:55], 11, v[66:67]
	v_lshl_add_u64 v[54:55], s[88:89], 0, v[54:55]
	v_lshl_add_u64 v[54:55], v[54:55], 0, v[2:3]
	global_store_dwordx4 v[54:55], v[44:47], off
	v_add_u32_e32 v50, 0xa0, v164
	v_mad_i64_i32 v[52:53], s[2:3], v50, s42, v[134:135]
	v_lshl_add_u64 v[52:53], v[52:53], 0, v[132:133]
	s_waitcnt vmcnt(15)
	v_mov_b32_e32 v48, v200
	v_mov_b32_e32 v49, v201
	v_cvt_f32_ubyte0_e32 v1, v48
	v_cvt_f32_ubyte0_e32 v44, v49
	v_cvt_f32_ubyte1_e32 v45, v48
	v_cvt_f32_ubyte1_e32 v46, v49
	v_cvt_f32_ubyte2_e32 v47, v48
	v_cvt_f32_ubyte2_e32 v51, v49
	v_cvt_f32_ubyte3_e32 v49, v49
	v_cvt_f32_ubyte3_e32 v48, v48
	v_max_f32_e32 v1, 1.0, v1
	v_max_f32_e32 v45, 1.0, v45
	v_max_f32_e32 v47, 1.0, v47
	v_max_f32_e32 v49, 1.0, v49
	v_max_f32_e32 v44, 1.0, v44
	v_max_f32_e32 v46, 1.0, v46
	v_max_f32_e32 v51, 1.0, v51
	v_max_f32_e32 v48, 1.0, v48
	v_mul_f32_e32 v1, 0x3b808081, v1
	v_mul_f32_e32 v45, 0x3b808081, v45
	v_mul_f32_e32 v47, 0x3b808081, v47
	v_mul_f32_e32 v49, 0x3b808081, v49
	v_mul_f32_e32 v44, 0x3b808081, v44
	v_mul_f32_e32 v46, 0x3b808081, v46
	v_mul_f32_e32 v51, 0x3b808081, v51
	v_mul_f32_e32 v48, 0x3b808081, v48
	v_mul_f32_e32 v1, v40, v1
	v_mul_f32_e32 v40, v41, v45
	v_mul_f32_e32 v41, v42, v47
	v_mul_f32_e32 v39, v39, v49
	v_mul_f32_e32 v42, v43, v48
	v_mul_f32_e32 v43, v36, v44
	v_mul_f32_e32 v44, v37, v46
	v_mul_f32_e32 v45, v38, v51
	v_cvt_pk_bf16_f32 v36, v1, v40
	v_cvt_pk_bf16_f32 v37, v41, v42
	v_cvt_pk_bf16_f32 v38, v43, v44
	v_cvt_pk_bf16_f32 v39, v45, v39
	v_ashrrev_i32_e32 v51, 31, v50
	global_store_dwordx4 v[54:55], v[36:39], off offset:256
	s_waitcnt vmcnt(15)
	v_mov_b32_e32 v40, v202
	v_mov_b32_e32 v41, v203
	v_cvt_f32_ubyte0_e32 v1, v40
	v_cvt_f32_ubyte0_e32 v36, v41
	v_cvt_f32_ubyte1_e32 v37, v40
	v_cvt_f32_ubyte1_e32 v38, v41
	v_cvt_f32_ubyte2_e32 v39, v40
	v_cvt_f32_ubyte2_e32 v42, v41
	v_cvt_f32_ubyte3_e32 v41, v41
	v_cvt_f32_ubyte3_e32 v40, v40
	v_max_f32_e32 v1, 1.0, v1
	v_max_f32_e32 v37, 1.0, v37
	v_max_f32_e32 v39, 1.0, v39
	v_max_f32_e32 v41, 1.0, v41
	v_max_f32_e32 v36, 1.0, v36
	v_max_f32_e32 v38, 1.0, v38
	v_max_f32_e32 v42, 1.0, v42
	v_max_f32_e32 v40, 1.0, v40
	v_mul_f32_e32 v1, 0x3b808081, v1
	v_mul_f32_e32 v37, 0x3b808081, v37
	v_mul_f32_e32 v39, 0x3b808081, v39
	v_mul_f32_e32 v41, 0x3b808081, v41
	v_mul_f32_e32 v36, 0x3b808081, v36
	v_mul_f32_e32 v38, 0x3b808081, v38
	v_mul_f32_e32 v42, 0x3b808081, v42
	v_mul_f32_e32 v40, 0x3b808081, v40
	v_mul_f32_e32 v1, v32, v1
	v_mul_f32_e32 v32, v33, v37
	v_mul_f32_e32 v33, v34, v39
	v_mul_f32_e32 v31, v31, v41
	v_mul_f32_e32 v34, v35, v40
	v_mul_f32_e32 v35, v28, v36
	v_mul_f32_e32 v36, v29, v38
	v_mul_f32_e32 v37, v30, v42
	v_cvt_pk_bf16_f32 v28, v1, v32
	v_cvt_pk_bf16_f32 v29, v33, v34
	v_cvt_pk_bf16_f32 v30, v35, v36
	v_cvt_pk_bf16_f32 v31, v37, v31
	v_lshlrev_b64 v[38:39], 11, v[50:51]
	v_lshl_add_u64 v[38:39], s[88:89], 0, v[38:39]
	v_lshl_add_u64 v[38:39], v[38:39], 0, v[2:3]
	global_store_dwordx4 v[38:39], v[28:31], off
	v_add_u32_e32 v34, 0xb0, v164
	v_mad_i64_i32 v[36:37], s[2:3], v34, s42, v[134:135]
	v_lshl_add_u64 v[36:37], v[36:37], 0, v[132:133]
	s_mov_b64 s[2:3], -1
	s_waitcnt vmcnt(15)
	v_mov_b32_e32 v32, v204
	v_mov_b32_e32 v33, v205
	v_cvt_f32_ubyte0_e32 v1, v32
	v_cvt_f32_ubyte0_e32 v28, v33
	v_cvt_f32_ubyte1_e32 v29, v32
	v_cvt_f32_ubyte1_e32 v30, v33
	v_cvt_f32_ubyte2_e32 v31, v32
	v_cvt_f32_ubyte2_e32 v35, v33
	v_cvt_f32_ubyte3_e32 v33, v33
	v_cvt_f32_ubyte3_e32 v32, v32
	v_max_f32_e32 v1, 1.0, v1
	v_max_f32_e32 v29, 1.0, v29
	v_max_f32_e32 v31, 1.0, v31
	v_max_f32_e32 v33, 1.0, v33
	v_max_f32_e32 v28, 1.0, v28
	v_max_f32_e32 v30, 1.0, v30
	v_max_f32_e32 v35, 1.0, v35
	v_max_f32_e32 v32, 1.0, v32
	v_mul_f32_e32 v1, 0x3b808081, v1
	v_mul_f32_e32 v29, 0x3b808081, v29
	v_mul_f32_e32 v31, 0x3b808081, v31
	v_mul_f32_e32 v33, 0x3b808081, v33
	v_mul_f32_e32 v28, 0x3b808081, v28
	v_mul_f32_e32 v30, 0x3b808081, v30
	v_mul_f32_e32 v35, 0x3b808081, v35
	v_mul_f32_e32 v32, 0x3b808081, v32
	v_mul_f32_e32 v1, v24, v1
	v_mul_f32_e32 v24, v25, v29
	v_mul_f32_e32 v25, v26, v31
	v_mul_f32_e32 v23, v23, v33
	v_mul_f32_e32 v26, v27, v32
	v_mul_f32_e32 v27, v20, v28
	v_mul_f32_e32 v28, v21, v30
	v_mul_f32_e32 v29, v22, v35
	v_cvt_pk_bf16_f32 v20, v1, v24
	v_cvt_pk_bf16_f32 v21, v25, v26
	v_cvt_pk_bf16_f32 v22, v27, v28
	v_cvt_pk_bf16_f32 v23, v29, v23
	v_ashrrev_i32_e32 v35, 31, v34
	global_store_dwordx4 v[38:39], v[20:23], off offset:256
	s_waitcnt vmcnt(15)
	v_mov_b32_e32 v24, v206
	v_mov_b32_e32 v25, v207
	v_cvt_f32_ubyte0_e32 v1, v24
	v_cvt_f32_ubyte0_e32 v20, v25
	v_cvt_f32_ubyte1_e32 v21, v24
	v_cvt_f32_ubyte1_e32 v22, v25
	v_cvt_f32_ubyte2_e32 v23, v24
	v_cvt_f32_ubyte2_e32 v26, v25
	v_cvt_f32_ubyte3_e32 v25, v25
	v_cvt_f32_ubyte3_e32 v24, v24
	v_max_f32_e32 v1, 1.0, v1
	v_max_f32_e32 v21, 1.0, v21
	v_max_f32_e32 v23, 1.0, v23
	v_max_f32_e32 v25, 1.0, v25
	v_max_f32_e32 v20, 1.0, v20
	v_max_f32_e32 v22, 1.0, v22
	v_max_f32_e32 v26, 1.0, v26
	v_max_f32_e32 v24, 1.0, v24
	v_mul_f32_e32 v1, 0x3b808081, v1
	v_mul_f32_e32 v21, 0x3b808081, v21
	v_mul_f32_e32 v23, 0x3b808081, v23
	v_mul_f32_e32 v25, 0x3b808081, v25
	v_mul_f32_e32 v20, 0x3b808081, v20
	v_mul_f32_e32 v22, 0x3b808081, v22
	v_mul_f32_e32 v26, 0x3b808081, v26
	v_mul_f32_e32 v24, 0x3b808081, v24
	v_mul_f32_e32 v1, v16, v1
	v_mul_f32_e32 v16, v17, v21
	v_mul_f32_e32 v17, v18, v23
	v_mul_f32_e32 v15, v15, v25
	v_mul_f32_e32 v18, v19, v24
	v_mul_f32_e32 v19, v12, v20
	v_mul_f32_e32 v20, v13, v22
	v_mul_f32_e32 v21, v14, v26
	v_cvt_pk_bf16_f32 v12, v1, v16
	v_cvt_pk_bf16_f32 v13, v17, v18
	v_cvt_pk_bf16_f32 v14, v19, v20
	v_cvt_pk_bf16_f32 v15, v21, v15
	v_lshlrev_b64 v[18:19], 11, v[34:35]
	v_lshl_add_u64 v[18:19], s[88:89], 0, v[18:19]
	v_lshl_add_u64 v[18:19], v[18:19], 0, v[2:3]
	global_store_dwordx4 v[18:19], v[12:15], off
	s_waitcnt vmcnt(15)
	v_mov_b32_e32 v16, v208
	v_mov_b32_e32 v17, v209
	v_cvt_f32_ubyte0_e32 v2, v17
	v_cvt_f32_ubyte1_e32 v3, v16
	v_cvt_f32_ubyte1_e32 v12, v17
	v_cvt_f32_ubyte0_e32 v1, v16
	v_cvt_f32_ubyte2_e32 v13, v16
	v_cvt_f32_ubyte2_e32 v14, v17
	v_cvt_f32_ubyte3_e32 v15, v16
	v_cvt_f32_ubyte3_e32 v16, v17
	v_max_f32_e32 v2, 1.0, v2
	v_max_f32_e32 v3, 1.0, v3
	v_max_f32_e32 v12, 1.0, v12
	v_max_f32_e32 v1, 1.0, v1
	v_max_f32_e32 v13, 1.0, v13
	v_max_f32_e32 v14, 1.0, v14
	v_max_f32_e32 v15, 1.0, v15
	v_max_f32_e32 v16, 1.0, v16
	v_mul_f32_e32 v2, 0x3b808081, v2
	v_mul_f32_e32 v3, 0x3b808081, v3
	v_mul_f32_e32 v12, 0x3b808081, v12
	v_mul_f32_e32 v1, 0x3b808081, v1
	v_mul_f32_e32 v13, 0x3b808081, v13
	v_mul_f32_e32 v14, 0x3b808081, v14
	v_mul_f32_e32 v15, 0x3b808081, v15
	v_mul_f32_e32 v16, 0x3b808081, v16
	v_mul_f32_e32 v3, v9, v3
	v_mul_f32_e32 v4, v4, v2
	v_mul_f32_e32 v5, v5, v12
	v_mul_f32_e32 v1, v8, v1
	v_mul_f32_e32 v8, v10, v13
	v_mul_f32_e32 v9, v11, v15
	v_mul_f32_e32 v6, v6, v14
	v_mul_f32_e32 v7, v7, v16
	v_cvt_pk_bf16_f32 v2, v1, v3
	v_cvt_pk_bf16_f32 v3, v8, v9
	v_cvt_pk_bf16_f32 v4, v4, v5
	v_cvt_pk_bf16_f32 v5, v6, v7
	global_store_dwordx4 v[18:19], v[2:5], off offset:256
	s_cbranch_vccnz .LBB0_804
	s_andn2_b64 vcc, exec, s[4:5]
	s_cbranch_vccnz .LBB0_803
	s_barrier
	s_branch .LBB0_803
